# GOUT to FFN1 and FFN1 to FFN2 grid barriers become 8-workgroup group barriers (closed producer/consumer groups; taken only when every workgroup sits on XCC c&7, else original barriers)
# baseline (speedup 1.0000x reference)
; __device__ __forceinline__ unsigned xb_ld(unsigned* p)              { return __hip_atomic_load(p, __ATOMIC_RELAXED, __HIP_MEMORY_SCOPE_AGENT); }
; __device__ __forceinline__ unsigned xb_add(unsigned* p, unsigned v) { return __hip_atomic_fetch_add(p, v, __ATOMIC_RELAXED, __HIP_MEMORY_SCOPE_AGENT); }
; __device__ __forceinline__ unsigned xb_xcc_id() { return (unsigned)__builtin_amdgcn_s_getreg((3 << 11) | 20) & 0xFu; }
.Lg1b_fin:
	s_waitcnt vmcnt(0) lgkmcnt(0)
	s_barrier
	s_cmp_lg_u32 s92, 0
	s_cbranch_scc1 .Lgb_guard_done
	s_getreg_b32 s0, hwreg(HW_REG_XCC_ID, 0, 4)
	v_readlane_b32 s1, v231, 0
	s_nop 3
	s_and_b32 s1, s1, 7
	s_cmp_eq_u32 s0, s1
	s_cbranch_scc1 .Lgb_guard_done
	s_load_dwordx2 s[4:5], s[88:89], 0xd0
	s_mov_b64 s[6:7], exec
	s_mov_b64 exec, 1
	v_mov_b32_e32 v0, 0
	v_mov_b32_e32 v1, 1
	s_waitcnt lgkmcnt(0)
	s_add_u32 s4, s4, 0x1fa03600
	s_addc_u32 s5, s5, 0
	global_atomic_add v0, v1, s[4:5]
	s_waitcnt vmcnt(0)
	s_mov_b64 exec, s[6:7]
.Lgb_guard_done:
	s_branch .LBB0_1163
	s_load_dword s0, s[88:89], 0xdc
	s_waitcnt lgkmcnt(0)
	s_cmp_lt_i32 s0, 11
	s_cbranch_scc1 .LBB0_1163
	s_getreg_b32 s0, hwreg(HW_REG_XCC_ID, 0, 4)
	s_cmp_lg_u32 s92, 0
	s_mov_b64 s[4:5], 0
	s_cbranch_scc1 .LBB0_1110
	v_mbcnt_lo_u32_b32 v0, -1, 0
	v_mbcnt_hi_u32_b32 v0, -1, v0
	s_nop 0
	v_cmp_eq_u32_e32 vcc, 0, v0
	s_and_b64 s[4:5], vcc, exec

; __device__ __forceinline__ unsigned xb_ld(unsigned* p)              { return __hip_atomic_load(p, __ATOMIC_RELAXED, __HIP_MEMORY_SCOPE_AGENT); }
; __device__ __forceinline__ unsigned xb_add(unsigned* p, unsigned v) { return __hip_atomic_fetch_add(p, v, __ATOMIC_RELAXED, __HIP_MEMORY_SCOPE_AGENT); }
; #define XB_SPIN(cond, bar) do { unsigned _sp = 0; while (cond) { __builtin_amdgcn_s_sleep(1); \
;     if ((++_sp & 255u) == 0u) { if (xb_ld(&(bar)[XB_TMO])) break; if (_sp > XB_SPIN_CAP) { atomicAdd(&(bar)[XB_TMO], 1u); break; } } } } while (0)
; __device__ __forceinline__ void xcd_barrier(const XcdBarrier& b, const bool leader, const unsigned G) {
;     asm volatile("s_waitcnt vmcnt(0)" ::: "memory");
;     __syncthreads();
;     if (leader) {
;         unsigned* bar = b.bar;
;         __builtin_amdgcn_s_waitcnt(0);
;         unsigned nloc = b.st[0], nx = b.st[1];
;         if (nloc == 0u) { xcd_barrier_complete(bar, b.x, G, nloc, nx); b.st[0] = nloc; b.st[1] = nx; }
;         const unsigned old = xb_add(&bar[XB_XSUB(b.x)], 1u);
;         const unsigned gen = old / nloc;
;         if (old + 1u == (gen + 1u) * nloc) {
;             __builtin_amdgcn_fence(__ATOMIC_RELEASE, "agent");
;             asm volatile("s_waitcnt vmcnt(0)" ::: "memory");
;             const unsigned og = xb_add(&bar[XB_TOP], 1u);
;             const unsigned tg = og / nx;
;             if (og + 1u == (tg + 1u) * nx) xb_add(&bar[XB_TOPGEN], 1u);
;             else XB_SPIN(xb_ld(&bar[XB_TOPGEN]) == tg, bar);
;             __builtin_amdgcn_fence(__ATOMIC_ACQUIRE, "agent");
;             xb_add(&bar[XB_XGEN(b.x)], 1u);
;             asm volatile("s_waitcnt vmcnt(0)" ::: "memory");
;         } else {
;             XB_SPIN(xb_ld(&bar[XB_XGEN(b.x)]) == gen, bar);
;             __builtin_amdgcn_fence(__ATOMIC_ACQUIRE, "agent");
;             asm volatile("s_waitcnt vmcnt(0)" ::: "memory");
;         }
.LBB0_1362:
	s_waitcnt vmcnt(0) lgkmcnt(0)
	s_load_dwordx2 s[4:5], s[88:89], 0xd0
	v_mov_b32_e32 v0, 0
	s_waitcnt lgkmcnt(0)
	s_add_u32 s4, s4, 0x1fa03600
	s_addc_u32 s5, s5, 0
	global_load_dword v1, v0, s[4:5] sc1
	s_waitcnt vmcnt(0)
	v_readfirstlane_b32 s0, v1
	s_nop 3
	s_cmp_lg_u32 s0, 0
	s_cbranch_scc1 .Lgb_slow_0
	s_barrier
	s_cmp_lg_u32 s92, 0
	s_cbranch_scc1 .Lgb_wait_0
	s_mov_b64 s[6:7], exec
	s_mov_b64 exec, 1
	v_readlane_b32 s0, v231, 0
	s_nop 3
	s_and_b32 s1, s0, 7
	s_lshr_b32 s0, s0, 3
	s_and_b32 s0, s0, 3
	s_lshl_b32 s1, s1, 2
	s_add_i32 s0, s0, s1
	s_lshl_b32 s0, s0, 6
	s_add_i32 s0, s0, 64
	v_mov_b32_e32 v0, s0
	v_mov_b32_e32 v1, 1
	global_atomic_add v2, v0, v1, s[4:5] sc0
	s_waitcnt vmcnt(0)
	v_readfirstlane_b32 s1, v2
	s_nop 3
	s_and_b32 s2, s1, 7
	s_cmp_eq_u32 s2, 7
	s_cbranch_scc1 .Lgb_done_0
	s_or_b32 s1, s1, 7
	s_mov_b32 s3, 0
.Lgb_spin_0:
	s_sleep 1
	global_load_dword v2, v0, s[4:5] sc1
	s_add_i32 s3, s3, 1
	s_waitcnt vmcnt(0)
	v_readfirstlane_b32 s2, v2
	s_nop 3
	s_cmp_gt_u32 s2, s1
	s_cbranch_scc1 .Lgb_done_0
	s_cmp_lt_u32 s3, 0x40000
	s_cbranch_scc1 .Lgb_spin_0
.Lgb_done_0:
	buffer_inv sc1
	s_waitcnt vmcnt(0)
	s_mov_b64 exec, s[6:7]
.Lgb_wait_0:
	s_barrier
	s_branch .LBB0_1418
